# diff attention right-of-diagonal tiles: 30 scalar v_sub pairs per tile replaced by 15 packed v_pk_add with neg modifiers (exact)
# speedup vs baseline: 1.0006x; 1.0006x over previous
; template <int MODE>
; DI void attn_unit(char* lds, const Params& p, int layer, int u) {
;     ...
;       if (MODE == 0) {
;         const float dbase = (float)(key0 + 4 * lh - qrow);
;         if (key0 > qlo + 31) { S0 = S0 - T0; S1 = S1 - T1; aoff = -slope2 * dbase; }
;         else if (key0 + 63 < qlo) { S0 = S0 + T0; S1 = S1 + T1; aoff = slope2 * dbase; }
;         else {
; #pragma unroll
;           for (int r = 0; r < 16; ++r) { const float cc = (float)((r & 3) + 8 * (r >> 2));
;             S0[r] = fmaf(-slope2, fabsf(dbase + cc), S0[r]); S1[r] = fmaf(-slope2, fabsf(dbase + cc + 32.f), S1[r]); }
;         }
.LBB0_630:
	s_andn2_saveexec_b64 s[68:69], s[68:69]
	s_cbranch_execz .LBB0_632
	s_nop 2
	v_pk_add_f32 v[46:47], v[94:95], v[136:137] neg_lo:[0,1] neg_hi:[0,1]
	v_pk_add_f32 v[44:45], v[92:93], v[134:135] neg_lo:[0,1] neg_hi:[0,1]
	v_pk_add_f32 v[42:43], v[90:91], v[132:133] neg_lo:[0,1] neg_hi:[0,1]
	v_pk_add_f32 v[40:41], v[88:89], v[130:131] neg_lo:[0,1] neg_hi:[0,1]
	v_pk_add_f32 v[38:39], v[86:87], v[128:129] neg_lo:[0,1] neg_hi:[0,1]
	v_pk_add_f32 v[36:37], v[84:85], v[126:127] neg_lo:[0,1] neg_hi:[0,1]
	v_pk_add_f32 v[34:35], v[82:83], v[124:125] neg_lo:[0,1] neg_hi:[0,1]
	v_sub_f32_e32 v33, v81, v119
	v_sub_f32_e32 v32, v80, v122
	v_pk_add_f32 v[62:63], v[78:79], v[138:139] neg_lo:[0,1] neg_hi:[0,1]
	v_pk_add_f32 v[60:61], v[76:77], v[140:141] neg_lo:[0,1] neg_hi:[0,1]
	v_pk_add_f32 v[58:59], v[74:75], v[142:143] neg_lo:[0,1] neg_hi:[0,1]
	v_pk_add_f32 v[56:57], v[72:73], v[144:145] neg_lo:[0,1] neg_hi:[0,1]
	v_pk_add_f32 v[54:55], v[70:71], v[146:147] neg_lo:[0,1] neg_hi:[0,1]
	v_pk_add_f32 v[52:53], v[68:69], v[148:149] neg_lo:[0,1] neg_hi:[0,1]
	v_pk_add_f32 v[50:51], v[66:67], v[150:151] neg_lo:[0,1] neg_hi:[0,1]
	v_pk_add_f32 v[48:49], v[64:65], v[152:153] neg_lo:[0,1] neg_hi:[0,1]
	s_nop 0
	v_mul_f32_e64 v162, -v119, v164
